# hgrn pass-1 cross-segment prefix loop unrolled by two with two register sets: next segment's state loads in flight while the current one is folded in
# baseline (speedup 1.0000x reference)
; #define LAS __attribute__((address_space(3)))
; __device__ __forceinline__ float fexp(float x) { return __builtin_amdgcn_exp2f(x * LOG2E); }
; __device__ __forceinline__ int opaque_tid() { int t = threadIdx.x; asm volatile("" : "+v"(t)); return t; }
; __device__ __forceinline__ void hgrn_item(const Params& p, int l, int item, int pass, LAS unsigned char* lds) {
;     const int tid = opaque_tid(), wid = tid >> 6, lane = tid & 63, fr = lane & 15, fq = lane >> 4;
;     const int b = item >> 5, hp = (item >> 4) & 1, seg = item & 15;
;     const int g4 = wid >> 2, wv = wid & 3, head = hp * 2 + g4;
;     LAS unsigned char* gb = lds + g4 * 8192;
;     LAS bf16_t* Qs = (LAS bf16_t*)gb; LAS bf16_t* Ks = (LAS bf16_t*)(gb + 2304); LAS bf16_t* KHt = (LAS bf16_t*)(gb + 4608);
;     LAS float* decs = (LAS float*)(gb + 6656); LAS float* ssq = (LAS float*)(gb + 6912);
;     const int kch = head * 64 + wv * 16 + fr;
;     const float lbv = p.lbs[l * 256 + kch];
;     const size_t iseg = ((size_t)b * 4 + head) * 16;
;     f32x4 S[4];
; #pragma unroll
;     for (int kt = 0; kt < 4; ++kt) S[kt] = ZERO4;
;     float segb = 0.f;
;     float ng[4] = {0.f, 0.f, 0.f, 0.f};
;     if (pass == 1) {
;         for (int s = 0; s < seg; ++s) { const float* Sp = p.hgS + (iseg + s) * 4096 + wv * 16 + fr; const float* Dp = p.hgD + (iseg + s) * 64;
; #pragma unroll
;             for (int kt = 0; kt < 4; ++kt) { const f32x4 dl = *(const f32x4*)(Dp + kt * 16 + fq * 4);
; #pragma unroll
;                 for (int j = 0; j < 4; ++j) S[kt][j] = fexp(dl[j]) * S[kt][j] + Sp[(kt * 16 + fq * 4 + j) * 64]; } }
.LBB0_327:
	v_mov_b32_e32 v25, v202
	s_lshr_b32 s0, s72, 6
	s_and_b32 s0, s0, 2
	v_ashrrev_i32_e32 v20, 8, v25
	v_lshrrev_b32_e32 v1, 2, v25
	v_and_b32_e32 v46, 15, v25
	v_add_u32_e32 v4, s0, v20
	v_and_b32_e32 v24, 48, v1
	v_lshlrev_b32_e32 v0, 6, v4
	v_or_b32_e32 v36, v24, v46
	v_or_b32_e32 v32, v36, v0
	v_add_u32_e32 v8, s28, v32
	v_mov_b32_e32 v6, s18
	v_mov_b32_e32 v7, s19
	v_ashrrev_i32_e32 v9, 31, v8
	v_lshl_add_u64 v[6:7], v[8:9], 2, v[6:7]
	global_load_dword v47, v[6:7], off
	s_ashr_i32 s18, s21, 5
	v_bfe_u32 v1, v25, 4, 2
	s_bfe_u32 s96, s72, 0x40003
	s_ashr_i32 s19, s18, 31
	s_cmp_lg_u32 s96, 0
	v_lshlrev_b32_e32 v22, 2, v1
	s_mov_b32 s22, 0x1a000
	s_mov_b32 s23, 0x17000
	s_mov_b32 s33, 0x19000
	s_cbranch_scc0 .LBB0_343
	v_ashrrev_i32_e32 v5, 31, v4
	s_lshl_b64 s[4:5], s[18:19], 6
	s_lshl_b32 s6, s72, 12
	v_lshl_add_u64 v[4:5], v[4:5], 4, s[4:5]
	s_lshl_b64 s[4:5], s[18:19], 20
	s_and_b32 s6, s6, 0x80000
	v_ashrrev_i32_e32 v21, 31, v20
	s_or_b32 s4, s4, s6
	v_lshlrev_b64 v[6:7], 18, v[20:21]
	v_lshl_add_u64 v[6:7], s[4:5], 0, v[6:7]
	v_and_b32_e32 v3, 48, v25
	v_lshlrev_b64 v[4:5], 8, v[4:5]
	v_lshl_or_b32 v6, v3, 6, v6
	v_and_b32_e32 v8, 0xc0, v25
	v_lshlrev_b32_e32 v9, 2, v46
	v_or_b32_e32 v4, v4, v3
	v_lshlrev_b32_e32 v28, 2, v1
	v_mov_b32_e32 v29, v2
	s_lshl_b32 s0, s72, 11
	v_or3_b32 v6, v6, v8, v9
	v_lshl_add_u64 v[4:5], s[12:13], 0, v[4:5]
	v_mov_b32_e32 v12, 0
	v_mov_b64_e32 v[26:27], v[28:29]
	s_and_b32 s0, s0, 0x3c000
	v_lshl_add_u64 v[30:31], s[10:11], 0, v[6:7]
	v_lshl_add_u64 v[34:35], v[4:5], 0, s[46:47]
	s_mov_b64 s[4:5], 0
	v_mov_b32_e32 v13, v12
	v_mov_b32_e32 v14, v12
	v_mov_b32_e32 v15, v12
	v_mov_b32_e32 v16, v12
	v_mov_b32_e32 v17, v12
	v_mov_b32_e32 v18, v12
	v_mov_b32_e32 v19, v12
	v_mov_b32_e32 v4, v12
	v_mov_b32_e32 v5, v12
	v_mov_b32_e32 v6, v12
	v_mov_b32_e32 v7, v12
	v_mov_b32_e32 v8, v12
	v_mov_b32_e32 v9, v12
	v_mov_b32_e32 v10, v12
	v_mov_b32_e32 v11, v12
	v_lshl_add_u64 v[56:57], v[30:31], 0, s[4:5]
	v_add_co_u32_e32 v58, vcc, s80, v56
	global_load_dwordx4 v[38:41], v[34:35], off offset:-128
	global_load_dwordx4 v[42:45], v[34:35], off offset:-64
	global_load_dwordx4 v[48:51], v[34:35], off
	global_load_dwordx4 v[52:55], v[34:35], off offset:64
	v_addc_co_u32_e32 v59, vcc, 0, v57, vcc
	v_add_co_u32_e32 v60, vcc, s81, v56
	s_add_u32 s4, s4, 0x4000
	s_nop 0
	v_addc_co_u32_e32 v61, vcc, 0, v57, vcc
	v_add_co_u32_e32 v62, vcc, s82, v56
	s_addc_u32 s5, s5, 0
	s_nop 0
	v_addc_co_u32_e32 v63, vcc, 0, v57, vcc
	global_load_dword v64, v[56:57], off
	global_load_dword v65, v[56:57], off offset:256
	global_load_dword v66, v[56:57], off offset:512
	global_load_dword v67, v[56:57], off offset:768
	s_nop 0
	global_load_dword v56, v[62:63], off
	global_load_dword v68, v[60:61], off
	global_load_dword v69, v[60:61], off offset:256
	global_load_dword v70, v[60:61], off offset:512
	global_load_dword v71, v[60:61], off offset:768
	global_load_dword v72, v[62:63], off offset:512
	global_load_dword v73, v[62:63], off offset:768
	global_load_dword v57, v[62:63], off offset:256
	s_nop 0
	global_load_dword v60, v[60:61], off offset:-4096
	s_nop 0
	global_load_dword v62, v[58:59], off offset:512
	global_load_dword v63, v[58:59], off offset:768
	global_load_dword v61, v[58:59], off offset:256
	v_lshl_add_u64 v[34:35], v[34:35], 0, s[48:49]
.LBB0_329:
	s_cmp_eq_u32 s0, s4
	s_cbranch_scc1 .Lhgp_lastA
	v_lshl_add_u64 v[134:135], v[30:31], 0, s[4:5]
	v_add_co_u32_e32 v140, vcc, s80, v134
	global_load_dwordx4 v[102:105], v[34:35], off offset:-128
	global_load_dwordx4 v[106:109], v[34:35], off offset:-64
	global_load_dwordx4 v[110:113], v[34:35], off
	global_load_dwordx4 v[114:117], v[34:35], off offset:64
	v_addc_co_u32_e32 v141, vcc, 0, v135, vcc
	v_add_co_u32_e32 v142, vcc, s81, v134
	s_add_u32 s4, s4, 0x4000
	s_nop 0
	v_addc_co_u32_e32 v143, vcc, 0, v135, vcc
	v_add_co_u32_e32 v146, vcc, s82, v134
	s_addc_u32 s5, s5, 0
	s_nop 0
	v_addc_co_u32_e32 v147, vcc, 0, v135, vcc
	global_load_dword v124, v[134:135], off
	global_load_dword v125, v[134:135], off offset:256
	global_load_dword v126, v[134:135], off offset:512
	global_load_dword v127, v[134:135], off offset:768
	s_nop 0
	global_load_dword v118, v[146:147], off
	global_load_dword v128, v[142:143], off
	global_load_dword v129, v[142:143], off offset:256
	global_load_dword v130, v[142:143], off offset:512
	global_load_dword v131, v[142:143], off offset:768
	global_load_dword v132, v[146:147], off offset:512
	global_load_dword v133, v[146:147], off offset:768
	global_load_dword v119, v[146:147], off offset:256
	s_nop 0
	global_load_dword v120, v[142:143], off offset:-4096
	s_nop 0
	global_load_dword v122, v[140:141], off offset:512
	global_load_dword v123, v[140:141], off offset:768
	global_load_dword v121, v[140:141], off offset:256
	v_lshl_add_u64 v[34:35], v[34:35], 0, s[48:49]
	s_waitcnt vmcnt(20)
	v_mul_f32_e32 v3, 0x3fb8aa3b, v38
	v_mul_f32_e32 v21, 0x3fb8aa3b, v39
	v_mul_f32_e32 v23, 0x3fb8aa3b, v40
	v_mul_f32_e32 v29, 0x3fb8aa3b, v41
	v_mul_f32_e32 v33, 0x3fb8aa3b, v42
	v_mul_f32_e32 v37, 0x3fb8aa3b, v43
	v_mul_f32_e32 v44, 0x3fb8aa3b, v44
	v_mul_f32_e32 v45, 0x3fb8aa3b, v45
	v_mul_f32_e32 v48, 0x3fb8aa3b, v48
	v_mul_f32_e32 v49, 0x3fb8aa3b, v49
	v_mul_f32_e32 v50, 0x3fb8aa3b, v50
	v_mul_f32_e32 v51, 0x3fb8aa3b, v51
	v_mul_f32_e32 v52, 0x3fb8aa3b, v52
	v_mul_f32_e32 v53, 0x3fb8aa3b, v53
	v_mul_f32_e32 v54, 0x3fb8aa3b, v54
	v_mul_f32_e32 v55, 0x3fb8aa3b, v55
	v_exp_f32_e32 v38, v3
	v_exp_f32_e32 v39, v21
	v_exp_f32_e32 v40, v23
	v_exp_f32_e32 v41, v29
	v_exp_f32_e32 v42, v33
	v_exp_f32_e32 v43, v37
	v_exp_f32_e32 v44, v44
	v_exp_f32_e32 v45, v45
	v_exp_f32_e32 v48, v48
	v_exp_f32_e32 v50, v50
	v_exp_f32_e32 v52, v52
	v_exp_f32_e32 v54, v54
	v_exp_f32_e32 v55, v55
	v_exp_f32_e32 v53, v53
	v_exp_f32_e32 v51, v51
	v_exp_f32_e32 v49, v49
	v_pk_fma_f32 v[10:11], v[10:11], v[54:55], v[72:73]
	v_pk_fma_f32 v[8:9], v[8:9], v[52:53], v[56:57]
	v_pk_fma_f32 v[6:7], v[6:7], v[50:51], v[70:71]
	v_pk_fma_f32 v[4:5], v[4:5], v[48:49], v[68:69]
	v_pk_fma_f32 v[18:19], v[18:19], v[44:45], v[62:63]
	v_pk_fma_f32 v[16:17], v[16:17], v[42:43], v[60:61]
	v_pk_fma_f32 v[14:15], v[14:15], v[40:41], v[66:67]
	v_pk_fma_f32 v[12:13], v[12:13], v[38:39], v[64:65]
	s_cmp_eq_u32 s0, s4
	s_cbranch_scc1 .Lhgp_lastB
; __device__ __forceinline__ float fexp(float x) { return __builtin_amdgcn_exp2f(x * LOG2E); }
; __device__ __forceinline__ void hgrn_item(const Params& p, int l, int item, int pass, LAS unsigned char* lds) {
;     ...
;         for (int s = 0; s < seg; ++s) { const float* Sp = p.hgS + (iseg + s) * 4096 + wv * 16 + fr; const float* Dp = p.hgD + (iseg + s) * 64;
; #pragma unroll
;             for (int kt = 0; kt < 4; ++kt) { const f32x4 dl = *(const f32x4*)(Dp + kt * 16 + fq * 4);
; #pragma unroll
;                 for (int j = 0; j < 4; ++j) S[kt][j] = fexp(dl[j]) * S[kt][j] + Sp[(kt * 16 + fq * 4 + j) * 64]; } }
	v_lshl_add_u64 v[56:57], v[30:31], 0, s[4:5]
	v_add_co_u32_e32 v58, vcc, s80, v56
	global_load_dwordx4 v[38:41], v[34:35], off offset:-128
	global_load_dwordx4 v[42:45], v[34:35], off offset:-64
	global_load_dwordx4 v[48:51], v[34:35], off
	global_load_dwordx4 v[52:55], v[34:35], off offset:64
	v_addc_co_u32_e32 v59, vcc, 0, v57, vcc
	v_add_co_u32_e32 v60, vcc, s81, v56
	s_add_u32 s4, s4, 0x4000
	s_nop 0
	v_addc_co_u32_e32 v61, vcc, 0, v57, vcc
	v_add_co_u32_e32 v62, vcc, s82, v56
	s_addc_u32 s5, s5, 0
	s_nop 0
	v_addc_co_u32_e32 v63, vcc, 0, v57, vcc
	global_load_dword v64, v[56:57], off
	global_load_dword v65, v[56:57], off offset:256
	global_load_dword v66, v[56:57], off offset:512
	global_load_dword v67, v[56:57], off offset:768
	s_nop 0
	global_load_dword v56, v[62:63], off
	global_load_dword v68, v[60:61], off
	global_load_dword v69, v[60:61], off offset:256
	global_load_dword v70, v[60:61], off offset:512
	global_load_dword v71, v[60:61], off offset:768
	global_load_dword v72, v[62:63], off offset:512
	global_load_dword v73, v[62:63], off offset:768
	global_load_dword v57, v[62:63], off offset:256
	s_nop 0
	global_load_dword v60, v[60:61], off offset:-4096
	s_nop 0
	global_load_dword v62, v[58:59], off offset:512
	global_load_dword v63, v[58:59], off offset:768
	global_load_dword v61, v[58:59], off offset:256
	v_lshl_add_u64 v[34:35], v[34:35], 0, s[48:49]
	s_waitcnt vmcnt(20)
	v_mul_f32_e32 v3, 0x3fb8aa3b, v102
	v_mul_f32_e32 v21, 0x3fb8aa3b, v103
	v_mul_f32_e32 v23, 0x3fb8aa3b, v104
	v_mul_f32_e32 v29, 0x3fb8aa3b, v105
	v_mul_f32_e32 v33, 0x3fb8aa3b, v106
	v_mul_f32_e32 v37, 0x3fb8aa3b, v107
	v_mul_f32_e32 v108, 0x3fb8aa3b, v108
	v_mul_f32_e32 v109, 0x3fb8aa3b, v109
	v_mul_f32_e32 v110, 0x3fb8aa3b, v110
	v_mul_f32_e32 v111, 0x3fb8aa3b, v111
	v_mul_f32_e32 v112, 0x3fb8aa3b, v112
	v_mul_f32_e32 v113, 0x3fb8aa3b, v113
	v_mul_f32_e32 v114, 0x3fb8aa3b, v114
	v_mul_f32_e32 v115, 0x3fb8aa3b, v115
	v_mul_f32_e32 v116, 0x3fb8aa3b, v116
	v_mul_f32_e32 v117, 0x3fb8aa3b, v117
	v_exp_f32_e32 v102, v3
	v_exp_f32_e32 v103, v21
	v_exp_f32_e32 v104, v23
	v_exp_f32_e32 v105, v29
	v_exp_f32_e32 v106, v33
	v_exp_f32_e32 v107, v37
	v_exp_f32_e32 v108, v108
	v_exp_f32_e32 v109, v109
	v_exp_f32_e32 v110, v110
	v_exp_f32_e32 v112, v112
	v_exp_f32_e32 v114, v114
	v_exp_f32_e32 v116, v116
	v_exp_f32_e32 v117, v117
	v_exp_f32_e32 v115, v115
	v_exp_f32_e32 v113, v113
	v_exp_f32_e32 v111, v111
	v_pk_fma_f32 v[10:11], v[10:11], v[116:117], v[132:133]
	v_pk_fma_f32 v[8:9], v[8:9], v[114:115], v[118:119]
	v_pk_fma_f32 v[6:7], v[6:7], v[112:113], v[130:131]
	v_pk_fma_f32 v[4:5], v[4:5], v[110:111], v[128:129]
	v_pk_fma_f32 v[18:19], v[18:19], v[108:109], v[122:123]
	v_pk_fma_f32 v[16:17], v[16:17], v[106:107], v[120:121]
	v_pk_fma_f32 v[14:15], v[14:15], v[104:105], v[126:127]
	v_pk_fma_f32 v[12:13], v[12:13], v[102:103], v[124:125]
	s_branch .LBB0_329
.Lhgp_lastA:
	s_waitcnt vmcnt(0)
	v_mul_f32_e32 v3, 0x3fb8aa3b, v38
	v_mul_f32_e32 v21, 0x3fb8aa3b, v39
	v_mul_f32_e32 v23, 0x3fb8aa3b, v40
	v_mul_f32_e32 v29, 0x3fb8aa3b, v41
	v_mul_f32_e32 v33, 0x3fb8aa3b, v42
	v_mul_f32_e32 v37, 0x3fb8aa3b, v43
	v_mul_f32_e32 v44, 0x3fb8aa3b, v44
	v_mul_f32_e32 v45, 0x3fb8aa3b, v45
	v_mul_f32_e32 v48, 0x3fb8aa3b, v48
	v_mul_f32_e32 v49, 0x3fb8aa3b, v49
	v_mul_f32_e32 v50, 0x3fb8aa3b, v50
	v_mul_f32_e32 v51, 0x3fb8aa3b, v51
	v_mul_f32_e32 v52, 0x3fb8aa3b, v52
	v_mul_f32_e32 v53, 0x3fb8aa3b, v53
	v_mul_f32_e32 v54, 0x3fb8aa3b, v54
	v_mul_f32_e32 v55, 0x3fb8aa3b, v55
	v_exp_f32_e32 v38, v3
	v_exp_f32_e32 v39, v21
	v_exp_f32_e32 v40, v23
	v_exp_f32_e32 v41, v29
	v_exp_f32_e32 v42, v33
	v_exp_f32_e32 v43, v37
	v_exp_f32_e32 v44, v44
	v_exp_f32_e32 v45, v45
	v_exp_f32_e32 v48, v48
	v_exp_f32_e32 v50, v50
	v_exp_f32_e32 v52, v52
	v_exp_f32_e32 v54, v54
	v_exp_f32_e32 v55, v55
	v_exp_f32_e32 v53, v53
	v_exp_f32_e32 v51, v51
	v_exp_f32_e32 v49, v49
	v_pk_fma_f32 v[10:11], v[10:11], v[54:55], v[72:73]
	v_pk_fma_f32 v[8:9], v[8:9], v[52:53], v[56:57]
	v_pk_fma_f32 v[6:7], v[6:7], v[50:51], v[70:71]
	v_pk_fma_f32 v[4:5], v[4:5], v[48:49], v[68:69]
	v_pk_fma_f32 v[18:19], v[18:19], v[44:45], v[62:63]
	v_pk_fma_f32 v[16:17], v[16:17], v[42:43], v[60:61]
	v_pk_fma_f32 v[14:15], v[14:15], v[40:41], v[66:67]
	v_pk_fma_f32 v[12:13], v[12:13], v[38:39], v[64:65]
	s_branch .Lhgp_done
.Lhgp_lastB:
	s_waitcnt vmcnt(0)
	v_mul_f32_e32 v3, 0x3fb8aa3b, v102
	v_mul_f32_e32 v21, 0x3fb8aa3b, v103
	v_mul_f32_e32 v23, 0x3fb8aa3b, v104
	v_mul_f32_e32 v29, 0x3fb8aa3b, v105
	v_mul_f32_e32 v33, 0x3fb8aa3b, v106
	v_mul_f32_e32 v37, 0x3fb8aa3b, v107
	v_mul_f32_e32 v108, 0x3fb8aa3b, v108
	v_mul_f32_e32 v109, 0x3fb8aa3b, v109
	v_mul_f32_e32 v110, 0x3fb8aa3b, v110
	v_mul_f32_e32 v111, 0x3fb8aa3b, v111
	v_mul_f32_e32 v112, 0x3fb8aa3b, v112
	v_mul_f32_e32 v113, 0x3fb8aa3b, v113
	v_mul_f32_e32 v114, 0x3fb8aa3b, v114
	v_mul_f32_e32 v115, 0x3fb8aa3b, v115
	v_mul_f32_e32 v116, 0x3fb8aa3b, v116
	v_mul_f32_e32 v117, 0x3fb8aa3b, v117
	v_exp_f32_e32 v102, v3
	v_exp_f32_e32 v103, v21
	v_exp_f32_e32 v104, v23
	v_exp_f32_e32 v105, v29
	v_exp_f32_e32 v106, v33
	v_exp_f32_e32 v107, v37
	v_exp_f32_e32 v108, v108
	v_exp_f32_e32 v109, v109
	v_exp_f32_e32 v110, v110
	v_exp_f32_e32 v112, v112
	v_exp_f32_e32 v114, v114
	v_exp_f32_e32 v116, v116
	v_exp_f32_e32 v117, v117
	v_exp_f32_e32 v115, v115
	v_exp_f32_e32 v113, v113
	v_exp_f32_e32 v111, v111
	v_pk_fma_f32 v[10:11], v[10:11], v[116:117], v[132:133]
	v_pk_fma_f32 v[8:9], v[8:9], v[114:115], v[118:119]
	v_pk_fma_f32 v[6:7], v[6:7], v[112:113], v[130:131]
	v_pk_fma_f32 v[4:5], v[4:5], v[110:111], v[128:129]
	v_pk_fma_f32 v[18:19], v[18:19], v[108:109], v[122:123]
	v_pk_fma_f32 v[16:17], v[16:17], v[106:107], v[120:121]
	v_pk_fma_f32 v[14:15], v[14:15], v[104:105], v[126:127]
	v_pk_fma_f32 v[12:13], v[12:13], v[102:103], v[124:125]
.Lhgp_done:
	v_mov_b64_e32 v[42:43], s[96:97]
	s_branch .LBB0_332
